# grid barrier: acquire invalidate issued at arrival instead of after the flag
# speedup vs baseline: 1.0086x; 1.0086x over previous
; __device__ __forceinline__ unsigned xb_ld(unsigned* p)              { return __hip_atomic_load(p, __ATOMIC_RELAXED, __HIP_MEMORY_SCOPE_AGENT); }
; __device__ __forceinline__ unsigned xb_add(unsigned* p, unsigned v) { return __hip_atomic_fetch_add(p, v, __ATOMIC_RELAXED, __HIP_MEMORY_SCOPE_AGENT); }
; #define XB_SPIN(cond, bar) do { unsigned _sp = 0; while (cond) { __builtin_amdgcn_s_sleep(1); \
;     if ((++_sp & 255u) == 0u) { if (xb_ld(&(bar)[XB_TMO])) break; if (_sp > XB_SPIN_CAP) { atomicAdd(&(bar)[XB_TMO], 1u); break; } } } } while (0)
; __device__ __forceinline__ void xcd_barrier(const XcdBarrier& b) {
;     ...
;         const unsigned old = xb_add(&bar[XB_XSUB(b.x)], 1u);
;         const unsigned gen = old / nloc;
;         if (old + 1u == (gen + 1u) * nloc) {
;             __builtin_amdgcn_fence(__ATOMIC_RELEASE, "agent");
;             asm volatile("s_waitcnt vmcnt(0)" ::: "memory");
;             const unsigned og = xb_add(&bar[XB_TOP], 1u);
;             const unsigned tg = og / nx;
;             if (og + 1u == (tg + 1u) * nx) xb_add(&bar[XB_TOPGEN], 1u);
;             else XB_SPIN(xb_ld(&bar[XB_TOPGEN]) == tg, bar);
;             __builtin_amdgcn_fence(__ATOMIC_ACQUIRE, "agent");
;             xb_add(&bar[XB_XGEN(b.x)], 1u);
;             asm volatile("s_waitcnt vmcnt(0)" ::: "memory");
;         } else {
;             XB_SPIN(xb_ld(&bar[XB_XGEN(b.x)]) == gen, bar);
.LBB0_145:
	s_or_b64 exec, exec, s[10:11]
	v_cvt_f32_u32_e32 v5, v3
	s_waitcnt vmcnt(0)
	v_readfirstlane_b32 s8, v4
	v_sub_u32_e32 v4, 0, v3
	v_rcp_iflag_f32_e32 v5, v5
	v_add_u32_e32 v6, s8, v2
	v_mul_f32_e32 v5, 0x4f7ffffe, v5
	v_cvt_u32_f32_e32 v5, v5
	v_mul_lo_u32 v2, v4, v5
	v_mul_hi_u32 v2, v5, v2
	v_add_u32_e32 v2, v5, v2
	v_mul_hi_u32 v2, v6, v2
	v_mul_lo_u32 v4, v2, v3
	v_sub_u32_e32 v4, v6, v4
	v_add_u32_e32 v5, 1, v2
	v_cmp_ge_u32_e32 vcc, v4, v3
	s_nop 1
	v_cndmask_b32_e32 v2, v2, v5, vcc
	v_sub_u32_e32 v5, v4, v3
	v_cndmask_b32_e32 v4, v4, v5, vcc
	v_add_u32_e32 v5, 1, v2
	v_cmp_ge_u32_e32 vcc, v4, v3
	v_add_u32_e32 v4, 1, v6
	s_nop 0
	v_cndmask_b32_e32 v2, v2, v5, vcc
	v_mul_lo_u32 v5, v3, v2
	v_add_u32_e32 v3, v5, v3
	v_cmp_ne_u32_e32 vcc, v4, v3
	s_and_saveexec_b64 s[8:9], vcc
	s_xor_b64 s[8:9], exec, s[8:9]
	s_cbranch_execz .LBB0_159
	buffer_inv sc1
	s_add_i32 s10, s28, 0x900
	s_mov_b32 s11, 0
	s_lshl_b64 s[10:11], s[10:11], 2
	s_add_u32 s14, s26, s10
	s_addc_u32 s15, s27, s11
	s_waitcnt lgkmcnt(0)
	v_mov_b32_e32 v1, 0
	global_load_dword v3, v1, s[14:15] sc1
	s_waitcnt vmcnt(0)
	v_cmp_eq_u32_e32 vcc, v3, v2
	s_and_saveexec_b64 s[10:11], vcc
	s_cbranch_execz .LBB0_158
	s_add_u32 s12, s6, 0xc0200
	s_addc_u32 s13, s7, 0
	s_mov_b32 s29, 1
	s_mov_b64 s[16:17], 0
	s_branch .LBB0_149

; __device__ __forceinline__ unsigned xb_ld(unsigned* p)              { return __hip_atomic_load(p, __ATOMIC_RELAXED, __HIP_MEMORY_SCOPE_AGENT); }
; __device__ __forceinline__ unsigned xb_add(unsigned* p, unsigned v) { return __hip_atomic_fetch_add(p, v, __ATOMIC_RELAXED, __HIP_MEMORY_SCOPE_AGENT); }
; #define XB_SPIN(cond, bar) do { unsigned _sp = 0; while (cond) { __builtin_amdgcn_s_sleep(1); \
;     if ((++_sp & 255u) == 0u) { if (xb_ld(&(bar)[XB_TMO])) break; if (_sp > XB_SPIN_CAP) { atomicAdd(&(bar)[XB_TMO], 1u); break; } } } } while (0)
; __device__ __forceinline__ void xcd_barrier(const XcdBarrier& b) {
;     ...
;             __builtin_amdgcn_fence(__ATOMIC_RELEASE, "agent");
;             asm volatile("s_waitcnt vmcnt(0)" ::: "memory");
;             const unsigned og = xb_add(&bar[XB_TOP], 1u);
;             const unsigned tg = og / nx;
;             if (og + 1u == (tg + 1u) * nx) xb_add(&bar[XB_TOPGEN], 1u);
;             else XB_SPIN(xb_ld(&bar[XB_TOPGEN]) == tg, bar);
;             __builtin_amdgcn_fence(__ATOMIC_ACQUIRE, "agent");
;             xb_add(&bar[XB_XGEN(b.x)], 1u);
;             asm volatile("s_waitcnt vmcnt(0)" ::: "memory");
;         } else {
;             XB_SPIN(xb_ld(&bar[XB_XGEN(b.x)]) == gen, bar);
;             __builtin_amdgcn_fence(__ATOMIC_ACQUIRE, "agent");
;             asm volatile("s_waitcnt vmcnt(0)" ::: "memory");
.LBB0_158:
	s_or_b64 exec, exec, s[10:11]
	s_waitcnt vmcnt(0)
	s_waitcnt vmcnt(0)
.LBB0_159:
	s_andn2_saveexec_b64 s[8:9], s[8:9]
	s_cbranch_execz .LBB0_179
	s_mov_b64 s[8:9], exec
	buffer_wbl2 sc1
	buffer_inv sc1
	s_waitcnt lgkmcnt(0)
	s_waitcnt vmcnt(0)
	v_mbcnt_lo_u32_b32 v2, s8, 0
	v_mbcnt_hi_u32_b32 v2, s9, v2
	v_cmp_eq_u32_e32 vcc, 0, v2
	s_and_saveexec_b64 s[10:11], vcc
	s_cbranch_execz .LBB0_162
	s_bcnt1_i32_b64 s8, s[8:9]
	v_mov_b32_e32 v3, 0xc3000
	v_mov_b32_e32 v4, s8
	global_atomic_add v3, v3, v4, s[6:7] offset:1024 sc0

; __device__ __forceinline__ unsigned xb_ld(unsigned* p)              { return __hip_atomic_load(p, __ATOMIC_RELAXED, __HIP_MEMORY_SCOPE_AGENT); }
; __device__ __forceinline__ unsigned xb_add(unsigned* p, unsigned v) { return __hip_atomic_fetch_add(p, v, __ATOMIC_RELAXED, __HIP_MEMORY_SCOPE_AGENT); }
; #define XB_SPIN(cond, bar) do { unsigned _sp = 0; while (cond) { __builtin_amdgcn_s_sleep(1); \
;     if ((++_sp & 255u) == 0u) { if (xb_ld(&(bar)[XB_TMO])) break; if (_sp > XB_SPIN_CAP) { atomicAdd(&(bar)[XB_TMO], 1u); break; } } } } while (0)
; __device__ __forceinline__ void xcd_barrier(const XcdBarrier& b) {
;     ...
;             if (og + 1u == (tg + 1u) * nx) xb_add(&bar[XB_TOPGEN], 1u);
;             else XB_SPIN(xb_ld(&bar[XB_TOPGEN]) == tg, bar);
;             __builtin_amdgcn_fence(__ATOMIC_ACQUIRE, "agent");
;             xb_add(&bar[XB_XGEN(b.x)], 1u);
;             asm volatile("s_waitcnt vmcnt(0)" ::: "memory");
.LBB0_176:
	s_or_b64 exec, exec, s[6:7]
	s_mov_b64 s[6:7], exec
	v_mbcnt_lo_u32_b32 v1, s6, 0
	v_mbcnt_hi_u32_b32 v1, s7, v1
	s_mov_b32 s11, 0
	v_cmp_eq_u32_e32 vcc, 0, v1
	s_waitcnt vmcnt(0)
	s_and_saveexec_b64 s[8:9], vcc
	s_cbranch_execz .LBB0_178
	s_add_i32 s10, s28, 0x900
	s_lshl_b64 s[10:11], s[10:11], 2
	s_add_u32 s10, s26, s10
	s_addc_u32 s11, s27, s11
	s_bcnt1_i32_b64 s6, s[6:7]
	v_mov_b32_e32 v1, 0
	v_mov_b32_e32 v2, s6
	global_atomic_add v1, v2, s[10:11]

; __device__ __forceinline__ unsigned xb_ld(unsigned* p)              { return __hip_atomic_load(p, __ATOMIC_RELAXED, __HIP_MEMORY_SCOPE_AGENT); }
; __device__ __forceinline__ unsigned xb_add(unsigned* p, unsigned v) { return __hip_atomic_fetch_add(p, v, __ATOMIC_RELAXED, __HIP_MEMORY_SCOPE_AGENT); }
; #define XB_SPIN(cond, bar) do { unsigned _sp = 0; while (cond) { __builtin_amdgcn_s_sleep(1); \
;     if ((++_sp & 255u) == 0u) { if (xb_ld(&(bar)[XB_TMO])) break; if (_sp > XB_SPIN_CAP) { atomicAdd(&(bar)[XB_TMO], 1u); break; } } } } while (0)
; __device__ __forceinline__ void xcd_barrier(const XcdBarrier& b) {
;     ...
;         const unsigned old = xb_add(&bar[XB_XSUB(b.x)], 1u);
;         const unsigned gen = old / nloc;
;         if (old + 1u == (gen + 1u) * nloc) {
;             __builtin_amdgcn_fence(__ATOMIC_RELEASE, "agent");
;             asm volatile("s_waitcnt vmcnt(0)" ::: "memory");
;             const unsigned og = xb_add(&bar[XB_TOP], 1u);
;             const unsigned tg = og / nx;
;             if (og + 1u == (tg + 1u) * nx) xb_add(&bar[XB_TOPGEN], 1u);
;             else XB_SPIN(xb_ld(&bar[XB_TOPGEN]) == tg, bar);
;             __builtin_amdgcn_fence(__ATOMIC_ACQUIRE, "agent");
;             xb_add(&bar[XB_XGEN(b.x)], 1u);
;             asm volatile("s_waitcnt vmcnt(0)" ::: "memory");
;         } else {
;             XB_SPIN(xb_ld(&bar[XB_XGEN(b.x)]) == gen, bar);
.LBB0_255:
	s_or_b64 exec, exec, s[10:11]
	v_cvt_f32_u32_e32 v6, v4
	s_waitcnt vmcnt(0)
	v_readfirstlane_b32 s8, v5
	v_sub_u32_e32 v5, 0, v4
	v_rcp_iflag_f32_e32 v6, v6
	v_add_u32_e32 v7, s8, v3
	v_mul_f32_e32 v6, 0x4f7ffffe, v6
	v_cvt_u32_f32_e32 v6, v6
	v_mul_lo_u32 v3, v5, v6
	v_mul_hi_u32 v3, v6, v3
	v_add_u32_e32 v3, v6, v3
	v_mul_hi_u32 v3, v7, v3
	v_mul_lo_u32 v5, v3, v4
	v_sub_u32_e32 v5, v7, v5
	v_add_u32_e32 v6, 1, v3
	v_cmp_ge_u32_e32 vcc, v5, v4
	s_nop 1
	v_cndmask_b32_e32 v3, v3, v6, vcc
	v_sub_u32_e32 v6, v5, v4
	v_cndmask_b32_e32 v5, v5, v6, vcc
	v_add_u32_e32 v6, 1, v3
	v_cmp_ge_u32_e32 vcc, v5, v4
	v_add_u32_e32 v5, 1, v7
	s_nop 0
	v_cndmask_b32_e32 v3, v3, v6, vcc
	v_mul_lo_u32 v6, v4, v3
	v_add_u32_e32 v4, v6, v4
	v_cmp_ne_u32_e32 vcc, v5, v4
	s_and_saveexec_b64 s[8:9], vcc
	s_xor_b64 s[8:9], exec, s[8:9]
	s_cbranch_execz .LBB0_269
	buffer_inv sc1
	s_add_i32 s10, s28, 0x900
	s_mov_b32 s11, 0
	s_lshl_b64 s[10:11], s[10:11], 2
	s_add_u32 s14, s26, s10
	s_addc_u32 s15, s27, s11
	s_waitcnt lgkmcnt(0)
	v_mov_b32_e32 v2, 0
	global_load_dword v4, v2, s[14:15] sc1
	s_waitcnt vmcnt(0)
	v_cmp_eq_u32_e32 vcc, v4, v3
	s_and_saveexec_b64 s[10:11], vcc
	s_cbranch_execz .LBB0_268
	s_add_u32 s12, s6, 0xc0200
	s_addc_u32 s13, s7, 0
	s_mov_b32 s29, 1
	s_mov_b64 s[16:17], 0
	s_branch .LBB0_259

; __device__ __forceinline__ unsigned xb_add(unsigned* p, unsigned v) { return __hip_atomic_fetch_add(p, v, __ATOMIC_RELAXED, __HIP_MEMORY_SCOPE_AGENT); }
; __device__ __forceinline__ void xcd_barrier(const XcdBarrier& b) {
;     ...
;             __builtin_amdgcn_fence(__ATOMIC_RELEASE, "agent");
;             asm volatile("s_waitcnt vmcnt(0)" ::: "memory");
;             const unsigned og = xb_add(&bar[XB_TOP], 1u);
.LBB0_269:
	s_andn2_saveexec_b64 s[8:9], s[8:9]
	s_cbranch_execz .LBB0_289
	s_mov_b64 s[8:9], exec
	buffer_wbl2 sc1
	buffer_inv sc1
	s_waitcnt lgkmcnt(0)
	s_waitcnt vmcnt(0)
	v_mbcnt_lo_u32_b32 v3, s8, 0
	v_mbcnt_hi_u32_b32 v3, s9, v3
	v_cmp_eq_u32_e32 vcc, 0, v3
	s_and_saveexec_b64 s[10:11], vcc
	s_cbranch_execz .LBB0_272
	s_bcnt1_i32_b64 s8, s[8:9]
	v_mov_b32_e32 v4, 0xc3000
	v_mov_b32_e32 v5, s8
	global_atomic_add v4, v4, v5, s[6:7] offset:1024 sc0

; __device__ __forceinline__ unsigned xb_ld(unsigned* p)              { return __hip_atomic_load(p, __ATOMIC_RELAXED, __HIP_MEMORY_SCOPE_AGENT); }
; __device__ __forceinline__ unsigned xb_add(unsigned* p, unsigned v) { return __hip_atomic_fetch_add(p, v, __ATOMIC_RELAXED, __HIP_MEMORY_SCOPE_AGENT); }
; #define XB_SPIN(cond, bar) do { unsigned _sp = 0; while (cond) { __builtin_amdgcn_s_sleep(1); \
;     if ((++_sp & 255u) == 0u) { if (xb_ld(&(bar)[XB_TMO])) break; if (_sp > XB_SPIN_CAP) { atomicAdd(&(bar)[XB_TMO], 1u); break; } } } } while (0)
; __device__ __forceinline__ void xcd_barrier(const XcdBarrier& b) {
;     ...
;             if (og + 1u == (tg + 1u) * nx) xb_add(&bar[XB_TOPGEN], 1u);
;             else XB_SPIN(xb_ld(&bar[XB_TOPGEN]) == tg, bar);
;             __builtin_amdgcn_fence(__ATOMIC_ACQUIRE, "agent");
;             xb_add(&bar[XB_XGEN(b.x)], 1u);
;             asm volatile("s_waitcnt vmcnt(0)" ::: "memory");
.LBB0_286:
	s_or_b64 exec, exec, s[6:7]
	s_mov_b64 s[6:7], exec
	v_mbcnt_lo_u32_b32 v2, s6, 0
	v_mbcnt_hi_u32_b32 v2, s7, v2
	s_mov_b32 s11, 0
	v_cmp_eq_u32_e32 vcc, 0, v2
	s_waitcnt vmcnt(0)
	s_and_saveexec_b64 s[8:9], vcc
	s_cbranch_execz .LBB0_288
	s_add_i32 s10, s28, 0x900
	s_lshl_b64 s[10:11], s[10:11], 2
	s_add_u32 s10, s26, s10
	s_addc_u32 s11, s27, s11
	s_bcnt1_i32_b64 s6, s[6:7]
	v_mov_b32_e32 v2, 0
	v_mov_b32_e32 v3, s6
	global_atomic_add v2, v3, s[10:11]

; __device__ __forceinline__ unsigned xb_ld(unsigned* p)              { return __hip_atomic_load(p, __ATOMIC_RELAXED, __HIP_MEMORY_SCOPE_AGENT); }
; __device__ __forceinline__ unsigned xb_add(unsigned* p, unsigned v) { return __hip_atomic_fetch_add(p, v, __ATOMIC_RELAXED, __HIP_MEMORY_SCOPE_AGENT); }
; #define XB_SPIN(cond, bar) do { unsigned _sp = 0; while (cond) { __builtin_amdgcn_s_sleep(1); \
;     if ((++_sp & 255u) == 0u) { if (xb_ld(&(bar)[XB_TMO])) break; if (_sp > XB_SPIN_CAP) { atomicAdd(&(bar)[XB_TMO], 1u); break; } } } } while (0)
; __device__ __forceinline__ void xcd_barrier(const XcdBarrier& b) {
;     ...
;         const unsigned old = xb_add(&bar[XB_XSUB(b.x)], 1u);
;         const unsigned gen = old / nloc;
;         if (old + 1u == (gen + 1u) * nloc) {
;             __builtin_amdgcn_fence(__ATOMIC_RELEASE, "agent");
;             asm volatile("s_waitcnt vmcnt(0)" ::: "memory");
;             const unsigned og = xb_add(&bar[XB_TOP], 1u);
;             const unsigned tg = og / nx;
;             if (og + 1u == (tg + 1u) * nx) xb_add(&bar[XB_TOPGEN], 1u);
;             else XB_SPIN(xb_ld(&bar[XB_TOPGEN]) == tg, bar);
;             __builtin_amdgcn_fence(__ATOMIC_ACQUIRE, "agent");
;             xb_add(&bar[XB_XGEN(b.x)], 1u);
;             asm volatile("s_waitcnt vmcnt(0)" ::: "memory");
;         } else {
;             XB_SPIN(xb_ld(&bar[XB_XGEN(b.x)]) == gen, bar);
.LBB0_1619:
	s_or_b64 exec, exec, s[16:17]
	v_cvt_f32_u32_e32 v6, v4
	s_waitcnt vmcnt(0)
	v_readfirstlane_b32 s10, v5
	v_sub_u32_e32 v5, 0, v4
	v_rcp_iflag_f32_e32 v6, v6
	v_add_u32_e32 v7, s10, v3
	v_mul_f32_e32 v6, 0x4f7ffffe, v6
	v_cvt_u32_f32_e32 v6, v6
	v_mul_lo_u32 v3, v5, v6
	v_mul_hi_u32 v3, v6, v3
	v_add_u32_e32 v3, v6, v3
	v_mul_hi_u32 v3, v7, v3
	v_mul_lo_u32 v5, v3, v4
	v_sub_u32_e32 v5, v7, v5
	v_add_u32_e32 v6, 1, v3
	v_cmp_ge_u32_e32 vcc, v5, v4
	s_nop 1
	v_cndmask_b32_e32 v3, v3, v6, vcc
	v_sub_u32_e32 v6, v5, v4
	v_cndmask_b32_e32 v5, v5, v6, vcc
	v_add_u32_e32 v6, 1, v3
	v_cmp_ge_u32_e32 vcc, v5, v4
	v_add_u32_e32 v5, 1, v7
	s_nop 0
	v_cndmask_b32_e32 v3, v3, v6, vcc
	v_mul_lo_u32 v6, v4, v3
	v_add_u32_e32 v4, v6, v4
	v_cmp_ne_u32_e32 vcc, v5, v4
	s_and_saveexec_b64 s[10:11], vcc
	s_xor_b64 s[10:11], exec, s[10:11]
	s_cbranch_execz .LBB0_1633
	buffer_inv sc1
	s_add_i32 s16, s36, 0x900
	s_mov_b32 s17, 0
	s_lshl_b64 s[16:17], s[16:17], 2
	s_add_u32 s20, s34, s16
	s_addc_u32 s21, s35, s17
	s_waitcnt lgkmcnt(0)
	v_mov_b32_e32 v2, 0
	global_load_dword v4, v2, s[20:21] sc1
	s_waitcnt vmcnt(0)
	v_cmp_eq_u32_e32 vcc, v4, v3
	s_and_saveexec_b64 s[16:17], vcc
	s_cbranch_execz .LBB0_1632
	s_add_u32 s18, s8, 0xc0200
	s_addc_u32 s19, s9, 0
	s_mov_b32 s37, 1
	s_mov_b64 s[22:23], 0
	s_branch .LBB0_1623

; __device__ __forceinline__ unsigned xb_ld(unsigned* p)              { return __hip_atomic_load(p, __ATOMIC_RELAXED, __HIP_MEMORY_SCOPE_AGENT); }
; __device__ __forceinline__ unsigned xb_add(unsigned* p, unsigned v) { return __hip_atomic_fetch_add(p, v, __ATOMIC_RELAXED, __HIP_MEMORY_SCOPE_AGENT); }
; #define XB_SPIN(cond, bar) do { unsigned _sp = 0; while (cond) { __builtin_amdgcn_s_sleep(1); \
;     if ((++_sp & 255u) == 0u) { if (xb_ld(&(bar)[XB_TMO])) break; if (_sp > XB_SPIN_CAP) { atomicAdd(&(bar)[XB_TMO], 1u); break; } } } } while (0)
; __device__ __forceinline__ void xcd_barrier(const XcdBarrier& b) {
;     ...
;             __builtin_amdgcn_fence(__ATOMIC_RELEASE, "agent");
;             asm volatile("s_waitcnt vmcnt(0)" ::: "memory");
;             const unsigned og = xb_add(&bar[XB_TOP], 1u);
;             const unsigned tg = og / nx;
;             if (og + 1u == (tg + 1u) * nx) xb_add(&bar[XB_TOPGEN], 1u);
;             else XB_SPIN(xb_ld(&bar[XB_TOPGEN]) == tg, bar);
;             __builtin_amdgcn_fence(__ATOMIC_ACQUIRE, "agent");
;             xb_add(&bar[XB_XGEN(b.x)], 1u);
;             asm volatile("s_waitcnt vmcnt(0)" ::: "memory");
;         } else {
;             XB_SPIN(xb_ld(&bar[XB_XGEN(b.x)]) == gen, bar);
;             __builtin_amdgcn_fence(__ATOMIC_ACQUIRE, "agent");
;             asm volatile("s_waitcnt vmcnt(0)" ::: "memory");
.LBB0_1632:
	s_or_b64 exec, exec, s[16:17]
	s_waitcnt vmcnt(0)
	s_waitcnt vmcnt(0)
.LBB0_1633:
	s_andn2_saveexec_b64 s[10:11], s[10:11]
	s_cbranch_execz .LBB0_1653
	s_mov_b64 s[10:11], exec
	buffer_wbl2 sc1
	buffer_inv sc1
	s_waitcnt lgkmcnt(0)
	s_waitcnt vmcnt(0)
	v_mbcnt_lo_u32_b32 v3, s10, 0
	v_mbcnt_hi_u32_b32 v3, s11, v3
	v_cmp_eq_u32_e32 vcc, 0, v3
	s_and_saveexec_b64 s[16:17], vcc
	s_cbranch_execz .LBB0_1636
	s_bcnt1_i32_b64 s10, s[10:11]
	v_mov_b32_e32 v4, 0xc3000
	v_mov_b32_e32 v5, s10
	global_atomic_add v4, v4, v5, s[8:9] offset:1024 sc0

; __device__ __forceinline__ unsigned xb_ld(unsigned* p)              { return __hip_atomic_load(p, __ATOMIC_RELAXED, __HIP_MEMORY_SCOPE_AGENT); }
; __device__ __forceinline__ unsigned xb_add(unsigned* p, unsigned v) { return __hip_atomic_fetch_add(p, v, __ATOMIC_RELAXED, __HIP_MEMORY_SCOPE_AGENT); }
; #define XB_SPIN(cond, bar) do { unsigned _sp = 0; while (cond) { __builtin_amdgcn_s_sleep(1); \
;     if ((++_sp & 255u) == 0u) { if (xb_ld(&(bar)[XB_TMO])) break; if (_sp > XB_SPIN_CAP) { atomicAdd(&(bar)[XB_TMO], 1u); break; } } } } while (0)
; __device__ __forceinline__ void xcd_barrier(const XcdBarrier& b) {
;     ...
;             if (og + 1u == (tg + 1u) * nx) xb_add(&bar[XB_TOPGEN], 1u);
;             else XB_SPIN(xb_ld(&bar[XB_TOPGEN]) == tg, bar);
;             __builtin_amdgcn_fence(__ATOMIC_ACQUIRE, "agent");
;             xb_add(&bar[XB_XGEN(b.x)], 1u);
;             asm volatile("s_waitcnt vmcnt(0)" ::: "memory");
.LBB0_1650:
	s_or_b64 exec, exec, s[8:9]
	s_mov_b64 s[8:9], exec
	v_mbcnt_lo_u32_b32 v2, s8, 0
	v_mbcnt_hi_u32_b32 v2, s9, v2
	s_mov_b32 s17, 0
	v_cmp_eq_u32_e32 vcc, 0, v2
	s_waitcnt vmcnt(0)
	s_and_saveexec_b64 s[10:11], vcc
	s_cbranch_execz .LBB0_1652
	s_add_i32 s16, s36, 0x900
	s_lshl_b64 s[16:17], s[16:17], 2
	s_add_u32 s16, s34, s16
	s_addc_u32 s17, s35, s17
	s_bcnt1_i32_b64 s8, s[8:9]
	v_mov_b32_e32 v2, 0
	v_mov_b32_e32 v3, s8
	global_atomic_add v2, v3, s[16:17]

; __device__ __forceinline__ unsigned xb_ld(unsigned* p)              { return __hip_atomic_load(p, __ATOMIC_RELAXED, __HIP_MEMORY_SCOPE_AGENT); }
; __device__ __forceinline__ unsigned xb_add(unsigned* p, unsigned v) { return __hip_atomic_fetch_add(p, v, __ATOMIC_RELAXED, __HIP_MEMORY_SCOPE_AGENT); }
; #define XB_SPIN(cond, bar) do { unsigned _sp = 0; while (cond) { __builtin_amdgcn_s_sleep(1); \
;     if ((++_sp & 255u) == 0u) { if (xb_ld(&(bar)[XB_TMO])) break; if (_sp > XB_SPIN_CAP) { atomicAdd(&(bar)[XB_TMO], 1u); break; } } } } while (0)
; __device__ __forceinline__ void xcd_barrier(const XcdBarrier& b) {
;     ...
;         const unsigned old = xb_add(&bar[XB_XSUB(b.x)], 1u);
;         const unsigned gen = old / nloc;
;         if (old + 1u == (gen + 1u) * nloc) {
;             __builtin_amdgcn_fence(__ATOMIC_RELEASE, "agent");
;             asm volatile("s_waitcnt vmcnt(0)" ::: "memory");
;             const unsigned og = xb_add(&bar[XB_TOP], 1u);
;             const unsigned tg = og / nx;
;             if (og + 1u == (tg + 1u) * nx) xb_add(&bar[XB_TOPGEN], 1u);
;             else XB_SPIN(xb_ld(&bar[XB_TOPGEN]) == tg, bar);
;             __builtin_amdgcn_fence(__ATOMIC_ACQUIRE, "agent");
;             xb_add(&bar[XB_XGEN(b.x)], 1u);
;             asm volatile("s_waitcnt vmcnt(0)" ::: "memory");
;         } else {
;             XB_SPIN(xb_ld(&bar[XB_XGEN(b.x)]) == gen, bar);
.LBB0_3173:
	s_or_b64 exec, exec, s[10:11]
	v_cvt_f32_u32_e32 v6, v4
	s_waitcnt vmcnt(0)
	v_readfirstlane_b32 s8, v5
	v_sub_u32_e32 v5, 0, v4
	v_rcp_iflag_f32_e32 v6, v6
	v_add_u32_e32 v7, s8, v3
	v_mul_f32_e32 v6, 0x4f7ffffe, v6
	v_cvt_u32_f32_e32 v6, v6
	v_mul_lo_u32 v3, v5, v6
	v_mul_hi_u32 v3, v6, v3
	v_add_u32_e32 v3, v6, v3
	v_mul_hi_u32 v3, v7, v3
	v_mul_lo_u32 v5, v3, v4
	v_sub_u32_e32 v5, v7, v5
	v_add_u32_e32 v6, 1, v3
	v_cmp_ge_u32_e32 vcc, v5, v4
	s_nop 1
	v_cndmask_b32_e32 v3, v3, v6, vcc
	v_sub_u32_e32 v6, v5, v4
	v_cndmask_b32_e32 v5, v5, v6, vcc
	v_add_u32_e32 v6, 1, v3
	v_cmp_ge_u32_e32 vcc, v5, v4
	v_add_u32_e32 v5, 1, v7
	s_nop 0
	v_cndmask_b32_e32 v3, v3, v6, vcc
	v_mul_lo_u32 v6, v4, v3
	v_add_u32_e32 v4, v6, v4
	v_cmp_ne_u32_e32 vcc, v5, v4
	s_and_saveexec_b64 s[8:9], vcc
	s_xor_b64 s[8:9], exec, s[8:9]
	s_cbranch_execz .LBB0_3187
	buffer_inv sc1
	s_add_i32 s10, s30, 0x900
	s_mov_b32 s11, 0
	s_lshl_b64 s[10:11], s[10:11], 2
	s_add_u32 s16, s28, s10
	s_addc_u32 s17, s29, s11
	s_waitcnt lgkmcnt(0)
	v_mov_b32_e32 v2, 0
	global_load_dword v4, v2, s[16:17] sc1
	s_waitcnt vmcnt(0)
	v_cmp_eq_u32_e32 vcc, v4, v3
	s_and_saveexec_b64 s[10:11], vcc
	s_cbranch_execz .LBB0_3186
	s_add_u32 s14, s6, 0xc0200
	s_addc_u32 s15, s7, 0
	s_mov_b32 s31, 1
	s_mov_b64 s[18:19], 0
	s_branch .LBB0_3177

; __device__ __forceinline__ unsigned xb_ld(unsigned* p)              { return __hip_atomic_load(p, __ATOMIC_RELAXED, __HIP_MEMORY_SCOPE_AGENT); }
; __device__ __forceinline__ unsigned xb_add(unsigned* p, unsigned v) { return __hip_atomic_fetch_add(p, v, __ATOMIC_RELAXED, __HIP_MEMORY_SCOPE_AGENT); }
; #define XB_SPIN(cond, bar) do { unsigned _sp = 0; while (cond) { __builtin_amdgcn_s_sleep(1); \
;     if ((++_sp & 255u) == 0u) { if (xb_ld(&(bar)[XB_TMO])) break; if (_sp > XB_SPIN_CAP) { atomicAdd(&(bar)[XB_TMO], 1u); break; } } } } while (0)
; __device__ __forceinline__ void xcd_barrier(const XcdBarrier& b) {
;     ...
;             if (og + 1u == (tg + 1u) * nx) xb_add(&bar[XB_TOPGEN], 1u);
;             else XB_SPIN(xb_ld(&bar[XB_TOPGEN]) == tg, bar);
;             __builtin_amdgcn_fence(__ATOMIC_ACQUIRE, "agent");
;             xb_add(&bar[XB_XGEN(b.x)], 1u);
;             asm volatile("s_waitcnt vmcnt(0)" ::: "memory");
.LBB0_3204:
	s_or_b64 exec, exec, s[6:7]
	s_mov_b64 s[6:7], exec
	v_mbcnt_lo_u32_b32 v2, s6, 0
	v_mbcnt_hi_u32_b32 v2, s7, v2
	s_mov_b32 s11, 0
	v_cmp_eq_u32_e32 vcc, 0, v2
	s_waitcnt vmcnt(0)
	s_and_saveexec_b64 s[8:9], vcc
	s_cbranch_execz .LBB0_3206
	s_add_i32 s10, s30, 0x900
	s_lshl_b64 s[10:11], s[10:11], 2
	s_add_u32 s10, s28, s10
	s_addc_u32 s11, s29, s11
	s_bcnt1_i32_b64 s6, s[6:7]
	v_mov_b32_e32 v2, 0
	v_mov_b32_e32 v3, s6
	global_atomic_add v2, v3, s[10:11]
